# LayerNorm 1: gamma/beta staged in LDS, chunks 1-6 of each row read them with ds_read_b128 instead of global loads
# speedup vs baseline: 1.0043x; 1.0041x over previous
; __device__ __forceinline__ int lane_id_v() { int l; asm volatile("v_mbcnt_lo_u32_b32 %0, -1, 0\n\tv_mbcnt_hi_u32_b32 %0, -1, %0" : "=v"(l)); return l; }
; __device__ __forceinline__ void p5_ln1(Frame& F, bool dummy) {
;     const int gw = F.bid * NWAVES + F.wave, NGW = F.G * NWAVES, lane = lane_id_v();
;     bf16* X1B = (bf16*)(F.ws + WS_A);
;     v4u wn[8];
; #pragma unroll
;     for (int k = 0; k < 8; ++k) wn[k] = *(const v4u*)(X1B + (size_t)gw * DM + 8 * (lane + 64 * k));
.LBB0_1476:
	s_cmp_lt_i32 s76, 7
	s_cselect_b64 s[0:1], -1, 0
	s_cmp_gt_i32 s77, 6
	s_cselect_b64 s[2:3], -1, 0
	s_and_b64 s[0:1], s[0:1], s[2:3]
	s_andn2_b64 vcc, exec, s[0:1]
	s_cbranch_vccnz .LBB0_1538
	s_lshl_b32 s0, s72, 3
	s_add_i32 s0, s74, s0
	s_cmpk_gt_i32 s0, 0x40ff
	v_mbcnt_lo_u32_b32 v0, -1, 0
	v_mbcnt_hi_u32_b32 v0, -1, v0
	s_cbranch_scc1 .LBB0_1482
	v_readlane_b32 s2, v253, 38
	v_readlane_b32 s3, v253, 39
	s_ashr_i32 s1, s0, 31
	v_readlane_b32 s8, v253, 32
	s_lshl_b32 s4, s2, 3
	s_lshl_b64 s[2:3], s[0:1], 13
	v_readlane_b32 s10, v253, 34
	v_lshlrev_b32_e32 v0, 3, v0
	v_readlane_b32 s11, v253, 35
	s_add_u32 s5, s10, s2
	v_add_u32_e32 v8, 0xe00, v0
	s_addc_u32 s7, s11, s3
	v_add_u32_e32 v6, 0xc00, v0
	v_ashrrev_i32_e32 v9, 31, v8
	s_add_u32 s6, s5, 0x4a00000
	v_add_u32_e32 v4, 0xa00, v0
	v_ashrrev_i32_e32 v7, 31, v6
	s_addc_u32 s7, s7, 0
	v_lshlrev_b64 v[10:11], 1, v[8:9]
	v_add_u32_e32 v2, 0x800, v0
	v_ashrrev_i32_e32 v5, 31, v4
	v_lshl_add_u64 v[12:13], s[6:7], 0, v[10:11]
	v_lshlrev_b64 v[14:15], 1, v[6:7]
	v_ashrrev_i32_e32 v3, 31, v2
	v_lshl_add_u64 v[16:17], s[6:7], 0, v[14:15]
	global_load_dwordx4 v[32:35], v[12:13], off
	global_load_dwordx4 v[36:39], v[16:17], off
	v_lshlrev_b64 v[12:13], 1, v[4:5]
	v_ashrrev_i32_e32 v1, 31, v0
	v_lshl_add_u64 v[16:17], s[6:7], 0, v[12:13]
	v_lshlrev_b64 v[18:19], 1, v[2:3]
	v_lshl_add_u64 v[20:21], s[6:7], 0, v[18:19]
	global_load_dwordx4 v[40:43], v[16:17], off
	global_load_dwordx4 v[44:47], v[20:21], off
	v_lshlrev_b64 v[16:17], 1, v[0:1]
	v_lshl_add_u64 v[20:21], s[6:7], 0, v[16:17]
	global_load_dwordx4 v[48:51], v[20:21], off offset:3072
	global_load_dwordx4 v[52:55], v[20:21], off offset:2048
	global_load_dwordx4 v[56:59], v[20:21], off offset:1024
	global_load_dwordx4 v[60:63], v[20:21], off
	v_readlane_b32 s12, v253, 16
	v_readlane_b32 s9, v253, 33
	v_readlane_b32 s14, v253, 18
	v_readlane_b32 s15, v253, 19
	v_readlane_b32 s26, v253, 30
	v_readlane_b32 s27, v253, 31
	v_add_u32_e32 v20, 0x400, v0
	s_ashr_i32 s5, s4, 31
	s_mov_b64 s[14:15], s[26:27]
	v_lshlrev_b64 v[2:3], 2, v[2:3]
	s_lshl_b64 s[8:9], s[0:1], 12
	v_ashrrev_i32_e32 v21, 31, v20
	v_add_u32_e32 v22, 0x600, v0
	s_lshl_b64 s[6:7], s[4:5], 13
	v_lshl_add_u64 v[76:77], s[14:15], 0, v[2:3]
	v_lshl_add_u64 v[78:79], s[80:81], 0, v[2:3]
	v_lshlrev_b64 v[2:3], 2, v[4:5]
	v_lshl_add_u64 v[92:93], s[8:9], 0, v[0:1]
	s_lshl_b64 s[8:9], s[4:5], 12
	v_ashrrev_i32_e32 v23, 31, v22
	v_readlane_b32 s13, v253, 17
	v_lshlrev_b64 v[20:21], 2, v[20:21]
	v_lshl_add_u64 v[80:81], s[14:15], 0, v[2:3]
	v_lshl_add_u64 v[82:83], s[80:81], 0, v[2:3]
	v_lshlrev_b64 v[2:3], 2, v[6:7]
	s_add_u32 s12, s6, s2
	v_lshlrev_b64 v[24:25], 2, v[0:1]
	v_lshl_add_u64 v[68:69], s[14:15], 0, v[20:21]
	v_lshl_add_u64 v[70:71], s[80:81], 0, v[20:21]
	v_lshlrev_b64 v[20:21], 2, v[22:23]
	v_lshl_add_u64 v[84:85], s[14:15], 0, v[2:3]
	v_lshl_add_u64 v[86:87], s[80:81], 0, v[2:3]
	v_lshlrev_b64 v[2:3], 2, v[8:9]
	s_addc_u32 s13, s7, s3
	v_lshl_add_u64 v[64:65], s[14:15], 0, v[24:25]
	v_lshl_add_u64 v[72:73], s[14:15], 0, v[20:21]
	v_lshl_add_u64 v[88:89], s[14:15], 0, v[2:3]
	v_lshl_add_u64 v[0:1], s[12:13], 0, v[16:17]
	s_mov_b64 s[14:15], 0x4a00800
	s_mov_b64 s[10:11], 0x4a00000
	v_lshl_add_u64 v[94:95], v[0:1], 0, s[14:15]
	v_lshl_add_u64 v[0:1], s[2:3], 0, v[10:11]
	v_lshl_add_u64 v[96:97], v[0:1], 0, s[10:11]
	v_lshl_add_u64 v[0:1], s[2:3], 0, v[14:15]
	v_lshl_add_u64 v[98:99], v[0:1], 0, s[10:11]
	v_lshl_add_u64 v[0:1], s[12:13], 0, v[18:19]
	v_lshl_add_u64 v[100:101], v[0:1], 0, s[10:11]
	v_lshl_add_u64 v[0:1], s[12:13], 0, v[12:13]
	v_lshl_add_u64 v[102:103], v[0:1], 0, s[10:11]
	v_lshl_add_u64 v[0:1], s[12:13], 0, v[14:15]
	v_lshl_add_u64 v[104:105], v[0:1], 0, s[10:11]
	v_lshl_add_u64 v[0:1], s[12:13], 0, v[10:11]
	v_lshl_add_u64 v[106:107], v[0:1], 0, s[10:11]
	v_lshl_add_u64 v[0:1], s[2:3], 0, v[18:19]
	v_lshl_add_u64 v[110:111], v[0:1], 0, s[10:11]
	v_lshl_add_u64 v[0:1], s[2:3], 0, v[12:13]
	v_lshl_add_u64 v[66:67], s[80:81], 0, v[24:25]
	v_lshl_add_u64 v[74:75], s[80:81], 0, v[20:21]
	v_lshl_add_u64 v[90:91], s[80:81], 0, v[2:3]
	v_lshl_add_u64 v[108:109], s[2:3], 0, v[16:17]
	v_lshl_add_u64 v[112:113], v[0:1], 0, s[10:11]
	s_mov_b32 s1, 0xffff0000
	v_mov_b32_e32 v150, 0x3727c5ac
	s_mov_b32 s2, 0x800000
	s_movk_i32 s3, 0x7fff
	s_mov_b32 s5, 0x4a00000
	s_mov_b32 s12, 0xc2fe0000
	s_mov_b32 s13, 0x40c0c00
	s_mov_b32 s14, 0x12e00000
	s_waitcnt vmcnt(0)
	v_mov_b64_e32 v[24:25], v[32:33]
	v_mov_b64_e32 v[28:29], v[36:37]
	s_mov_b32 s15, 0xc0c0500
	v_mov_b32_e32 v151, 0x42fe0000
	v_mov_b64_e32 v[26:27], v[34:35]
	v_mov_b64_e32 v[30:31], v[38:39]
	v_mov_b64_e32 v[16:17], v[40:41]
	v_mov_b64_e32 v[20:21], v[44:45]
	v_mov_b64_e32 v[0:1], v[48:49]
	v_mov_b64_e32 v[4:5], v[52:53]
	v_mov_b64_e32 v[8:9], v[56:57]
	v_mov_b64_e32 v[12:13], v[60:61]
	v_mov_b64_e32 v[18:19], v[42:43]
	v_mov_b64_e32 v[22:23], v[46:47]
	v_mov_b64_e32 v[2:3], v[50:51]
	v_mov_b64_e32 v[6:7], v[54:55]
	v_mov_b64_e32 v[10:11], v[58:59]
	v_mov_b64_e32 v[14:15], v[62:63]
	v_readlane_b32 s16, v253, 20
	v_readlane_b32 s17, v253, 21
	v_readlane_b32 s18, v253, 22
	v_readlane_b32 s19, v253, 23
	v_readlane_b32 s20, v253, 24
	v_readlane_b32 s21, v253, 25
	v_readlane_b32 s22, v253, 26
	v_readlane_b32 s23, v253, 27
	v_readlane_b32 s24, v253, 28
	v_readlane_b32 s25, v253, 29
	s_lshl_b32 s28, s74, 11
	s_mov_b32 s29, 0
	v_lshl_add_u64 v[232:233], v[64:65], 0, s[28:29]
	v_lshl_add_u64 v[234:235], v[66:67], 0, s[28:29]
	global_load_dwordx4 v[236:239], v[232:233], off
	global_load_dwordx4 v[240:243], v[232:233], off offset:16
	global_load_dwordx4 v[244:247], v[234:235], off
	global_load_dwordx4 v[248:251], v[234:235], off offset:16
	v_mbcnt_lo_u32_b32 v252, -1, 0
	v_mbcnt_hi_u32_b32 v252, -1, v252
	v_lshlrev_b32_e32 v252, 5, v252
	v_add_u32_e32 v254, s28, v252
	s_waitcnt vmcnt(0)
	ds_write_b128 v254, v[236:239]
	ds_write_b128 v254, v[240:243] offset:16
	ds_write_b128 v254, v[244:247] offset:16384
	ds_write_b128 v254, v[248:251] offset:16400
	s_waitcnt lgkmcnt(0)
	s_barrier
	s_branch .LBB0_1480
; __device__ __forceinline__ void p5_ln1(Frame& F, bool dummy) {
;     ...
;         bf16* xr = X1B + (size_t)m * DM; float v[8][8]; float s = 0.f;
; #pragma unroll
;         for (int k = 0; k < 8; ++k) { const unsigned ww[4] = {wn[k].x, wn[k].y, wn[k].z, wn[k].w};
; #pragma unroll
;             for (int e = 0; e < 4; ++e) { v[k][2 * e] = __uint_as_float(ww[e] << 16); v[k][2 * e + 1] = __uint_as_float(ww[e] & 0xffff0000u); s += v[k][2 * e] + v[k][2 * e + 1]; } }
;         if (m + NGW < MTOK) {
; #pragma unroll
;             for (int k = 0; k < 8; ++k) wn[k] = *(const v4u*)(xr + (size_t)NGW * DM + 8 * (lane + 64 * k)); }
;         const float mean = wave_sum(s) * (1.f / DM); float s2 = 0.f;
.LBB0_1479:
	v_lshlrev_b32_e32 v117, 16, v61
	v_lshlrev_b32_e32 v116, 16, v60
	v_and_b32_e32 v121, 0xffff0000, v61
	v_and_b32_e32 v120, 0xffff0000, v60
	v_pk_add_f32 v[60:61], v[116:117], v[120:121]
	v_lshlrev_b32_e32 v115, 16, v63
	v_add_f32_e32 v60, 0, v60
	v_lshlrev_b32_e32 v114, 16, v62
	v_and_b32_e32 v119, 0xffff0000, v63
	v_and_b32_e32 v118, 0xffff0000, v62
	v_add_f32_e32 v122, v61, v60
	v_pk_add_f32 v[60:61], v[114:115], v[118:119]
	v_and_b32_e32 v63, 0xffff0000, v57
	v_add_f32_e32 v60, v60, v122
	v_add_f32_e32 v122, v61, v60
	v_lshlrev_b32_e32 v61, 16, v57
	v_lshlrev_b32_e32 v60, 16, v56
	v_and_b32_e32 v62, 0xffff0000, v56
	v_pk_add_f32 v[56:57], v[60:61], v[62:63]
	v_lshlrev_b32_e32 v123, 16, v59
	v_add_f32_e32 v56, v56, v122
	v_lshlrev_b32_e32 v122, 16, v58
	v_and_b32_e32 v125, 0xffff0000, v59
	v_and_b32_e32 v124, 0xffff0000, v58
	v_add_f32_e32 v126, v57, v56
	v_pk_add_f32 v[56:57], v[122:123], v[124:125]
	v_lshlrev_b32_e32 v127, 16, v53
	v_add_f32_e32 v56, v56, v126
	v_lshlrev_b32_e32 v126, 16, v52
	v_and_b32_e32 v129, 0xffff0000, v53
	v_and_b32_e32 v128, 0xffff0000, v52
	v_add_f32_e32 v56, v57, v56
	v_pk_add_f32 v[52:53], v[126:127], v[128:129]
	v_lshlrev_b32_e32 v131, 16, v55
	v_add_f32_e32 v52, v52, v56
	v_lshlrev_b32_e32 v130, 16, v54
	v_and_b32_e32 v133, 0xffff0000, v55
	v_and_b32_e32 v132, 0xffff0000, v54
	v_add_f32_e32 v56, v53, v52
	v_pk_add_f32 v[52:53], v[130:131], v[132:133]
	v_lshlrev_b32_e32 v157, 16, v49
	v_add_f32_e32 v52, v52, v56
	v_lshlrev_b32_e32 v156, 16, v48
	v_and_b32_e32 v159, 0xffff0000, v49
	v_and_b32_e32 v158, 0xffff0000, v48
	v_add_f32_e32 v52, v53, v52
	v_pk_add_f32 v[48:49], v[156:157], v[158:159]
	v_lshlrev_b32_e32 v161, 16, v51
	v_add_f32_e32 v48, v48, v52
	v_add_f32_e32 v136, v49, v48
	v_lshlrev_b32_e32 v160, 16, v50
	v_and_b32_e32 v163, 0xffff0000, v51
	v_and_b32_e32 v162, 0xffff0000, v50
	global_load_dwordx4 v[48:51], v[64:65], off offset:16
	global_load_dwordx4 v[52:55], v[64:65], off
	v_pk_add_f32 v[134:135], v[160:161], v[162:163]
	global_load_dwordx4 v[56:59], v[66:67], off
	global_load_dwordx4 v[152:155], v[66:67], off offset:16
	v_add_f32_e32 v134, v134, v136
	v_lshlrev_b32_e32 v165, 16, v45
	v_lshlrev_b32_e32 v164, 16, v44
	v_and_b32_e32 v45, 0xffff0000, v45
	v_and_b32_e32 v44, 0xffff0000, v44
	v_add_f32_e32 v136, v135, v134
	v_pk_add_f32 v[134:135], v[164:165], v[44:45]
	v_lshlrev_b32_e32 v167, 16, v47
	v_add_f32_e32 v134, v134, v136
	v_lshlrev_b32_e32 v166, 16, v46
	v_and_b32_e32 v47, 0xffff0000, v47
	v_and_b32_e32 v46, 0xffff0000, v46
	v_add_f32_e32 v136, v135, v134
	v_pk_add_f32 v[134:135], v[166:167], v[46:47]
	v_lshlrev_b32_e32 v169, 16, v41
	v_add_f32_e32 v134, v134, v136
	v_lshlrev_b32_e32 v168, 16, v40
	v_and_b32_e32 v41, 0xffff0000, v41
	v_and_b32_e32 v40, 0xffff0000, v40
	v_add_f32_e32 v136, v135, v134
	v_pk_add_f32 v[134:135], v[168:169], v[40:41]
	v_lshlrev_b32_e32 v171, 16, v43
	v_add_f32_e32 v134, v134, v136
	v_lshlrev_b32_e32 v170, 16, v42
	v_and_b32_e32 v43, 0xffff0000, v43
	v_and_b32_e32 v42, 0xffff0000, v42
	v_add_f32_e32 v136, v135, v134
	v_pk_add_f32 v[134:135], v[170:171], v[42:43]
	v_lshlrev_b32_e32 v173, 16, v37
	v_add_f32_e32 v134, v134, v136
	v_lshlrev_b32_e32 v172, 16, v36
	v_and_b32_e32 v37, 0xffff0000, v37
	v_and_b32_e32 v36, 0xffff0000, v36
	v_add_f32_e32 v136, v135, v134
	v_pk_add_f32 v[134:135], v[172:173], v[36:37]
	v_lshlrev_b32_e32 v175, 16, v39
	v_add_f32_e32 v134, v134, v136
	v_lshlrev_b32_e32 v174, 16, v38
	v_and_b32_e32 v39, 0xffff0000, v39
	v_and_b32_e32 v38, 0xffff0000, v38
	v_add_f32_e32 v136, v135, v134
	v_pk_add_f32 v[134:135], v[174:175], v[38:39]
	v_lshlrev_b32_e32 v177, 16, v33
	v_add_f32_e32 v134, v134, v136
	v_lshlrev_b32_e32 v176, 16, v32
	v_and_b32_e32 v33, 0xffff0000, v33
	v_and_b32_e32 v32, 0xffff0000, v32
	v_add_f32_e32 v136, v135, v134
	v_pk_add_f32 v[134:135], v[176:177], v[32:33]
	v_lshlrev_b32_e32 v179, 16, v35
	v_add_f32_e32 v134, v134, v136
	v_lshlrev_b32_e32 v178, 16, v34
	v_and_b32_e32 v181, 0xffff0000, v35
	v_and_b32_e32 v180, 0xffff0000, v34
	v_add_f32_e32 v134, v135, v134
	v_pk_add_f32 v[34:35], v[178:179], v[180:181]
	v_readlane_b32 s16, v253, 32
	v_add_f32_e32 v34, v34, v134
	v_add_f32_e32 v34, v35, v34
	v_readlane_b32 s18, v253, 34
	v_readlane_b32 s19, v253, 35
	v_add_f32_dpp v34, v34, v34 quad_perm:[1,0,3,2] row_mask:0xf bank_mask:0xf bound_ctrl:1
	v_lshl_add_u64 v[94:95], v[94:95], 0, s[6:7]
	v_lshl_add_u64 v[100:101], v[100:101], 0, s[6:7]
	v_add_f32_dpp v34, v34, v34 quad_perm:[2,3,0,1] row_mask:0xf bank_mask:0xf bound_ctrl:1
	v_lshl_add_u64 v[102:103], v[102:103], 0, s[6:7]
	v_lshl_add_u64 v[104:105], v[104:105], 0, s[6:7]
	v_add_f32_dpp v34, v34, v34 row_half_mirror row_mask:0xf bank_mask:0xf bound_ctrl:1
	v_lshl_add_u64 v[106:107], v[106:107], 0, s[6:7]
	v_readlane_b32 s17, v253, 33
	v_add_f32_dpp v34, v34, v34 row_ror:8 row_mask:0xf bank_mask:0xf bound_ctrl:1
	ds_swizzle_b32 v35, v34 offset:swizzle(SWAP,16)
	s_waitcnt vmcnt(3)
	v_mov_b32_e32 v204, v48
	s_waitcnt lgkmcnt(0)
; __device__ __forceinline__ void p5_ln1(Frame& F, bool dummy) {
;     ...
;         const float mean = wave_sum(s) * (1.f / DM); float s2 = 0.f;
; #pragma unroll
;         for (int k = 0; k < 8; ++k)
; #pragma unroll
;             for (int e = 0; e < 8; ++e) { v[k][e] -= mean; s2 += v[k][e] * v[k][e]; }
;         const float rstd = rsqrtf(wave_sum(s2) * (1.f / DM) + LN_EPS);
	v_add_f32_e32 v34, v34, v35
	v_mov_b32_e32 v35, v34
	s_nop 1
	v_permlane32_swap_b32_e32 v34, v35
	v_add_f32_e32 v34, v34, v35
	v_mul_f32_e32 v182, 0x39800000, v34
	v_pk_add_f32 v[184:185], v[116:117], v[182:183] op_sel_hi:[1,0] neg_lo:[0,1] neg_hi:[0,1]
	v_pk_add_f32 v[188:189], v[120:121], v[182:183] op_sel_hi:[1,0] neg_lo:[0,1] neg_hi:[0,1]
	v_pk_mul_f32 v[186:187], v[184:185], v[184:185]
	v_pk_mul_f32 v[190:191], v[188:189], v[188:189]
	v_pk_add_f32 v[196:197], v[114:115], v[182:183] op_sel_hi:[1,0] neg_lo:[0,1] neg_hi:[0,1]
	v_add_f32_e32 v48, v186, v190
	v_add_f32_e32 v48, v187, v48
	v_pk_mul_f32 v[198:199], v[196:197], v[196:197]
	v_pk_add_f32 v[200:201], v[118:119], v[182:183] op_sel_hi:[1,0] neg_lo:[0,1] neg_hi:[0,1]
	v_add_f32_e32 v48, v191, v48
	v_pk_mul_f32 v[202:203], v[200:201], v[200:201]
	v_add_f32_e32 v48, v198, v48
	v_add_f32_e32 v48, v202, v48
	v_pk_add_f32 v[148:149], v[60:61], v[182:183] op_sel_hi:[1,0] neg_lo:[0,1] neg_hi:[0,1]
	v_add_f32_e32 v48, v199, v48
	v_pk_mul_f32 v[206:207], v[148:149], v[148:149]
	v_pk_add_f32 v[146:147], v[62:63], v[182:183] op_sel_hi:[1,0] neg_lo:[0,1] neg_hi:[0,1]
	v_add_f32_e32 v48, v203, v48
	v_pk_mul_f32 v[208:209], v[146:147], v[146:147]
	v_add_f32_e32 v48, v206, v48
	v_add_f32_e32 v48, v208, v48
	v_pk_add_f32 v[144:145], v[122:123], v[182:183] op_sel_hi:[1,0] neg_lo:[0,1] neg_hi:[0,1]
	v_add_f32_e32 v48, v207, v48
	v_pk_mul_f32 v[210:211], v[144:145], v[144:145]
	v_pk_add_f32 v[142:143], v[124:125], v[182:183] op_sel_hi:[1,0] neg_lo:[0,1] neg_hi:[0,1]
	v_add_f32_e32 v48, v209, v48
	v_pk_mul_f32 v[212:213], v[142:143], v[142:143]
	v_add_f32_e32 v48, v210, v48
	v_add_f32_e32 v48, v212, v48
	v_pk_add_f32 v[140:141], v[126:127], v[182:183] op_sel_hi:[1,0] neg_lo:[0,1] neg_hi:[0,1]
	v_add_f32_e32 v48, v211, v48
	v_pk_mul_f32 v[214:215], v[140:141], v[140:141]
	v_pk_add_f32 v[138:139], v[128:129], v[182:183] op_sel_hi:[1,0] neg_lo:[0,1] neg_hi:[0,1]
	v_add_f32_e32 v48, v213, v48
	v_pk_mul_f32 v[216:217], v[138:139], v[138:139]
	v_add_f32_e32 v48, v214, v48
	v_add_f32_e32 v48, v216, v48
	v_pk_add_f32 v[136:137], v[130:131], v[182:183] op_sel_hi:[1,0] neg_lo:[0,1] neg_hi:[0,1]
	v_add_f32_e32 v48, v215, v48
	v_pk_mul_f32 v[218:219], v[136:137], v[136:137]
	v_pk_add_f32 v[134:135], v[132:133], v[182:183] op_sel_hi:[1,0] neg_lo:[0,1] neg_hi:[0,1]
	v_add_f32_e32 v48, v217, v48
	v_pk_mul_f32 v[220:221], v[134:135], v[134:135]
	v_add_f32_e32 v48, v218, v48
	v_add_f32_e32 v48, v220, v48
	v_pk_add_f32 v[132:133], v[156:157], v[182:183] op_sel_hi:[1,0] neg_lo:[0,1] neg_hi:[0,1]
	v_add_f32_e32 v48, v219, v48
	v_pk_mul_f32 v[156:157], v[132:133], v[132:133]
	v_pk_add_f32 v[130:131], v[158:159], v[182:183] op_sel_hi:[1,0] neg_lo:[0,1] neg_hi:[0,1]
	v_add_f32_e32 v48, v221, v48
	v_pk_mul_f32 v[158:159], v[130:131], v[130:131]
	v_add_f32_e32 v48, v156, v48
	v_add_f32_e32 v48, v158, v48
	v_pk_add_f32 v[128:129], v[160:161], v[182:183] op_sel_hi:[1,0] neg_lo:[0,1] neg_hi:[0,1]
	v_add_f32_e32 v48, v157, v48
	v_pk_mul_f32 v[160:161], v[128:129], v[128:129]
	v_pk_add_f32 v[126:127], v[162:163], v[182:183] op_sel_hi:[1,0] neg_lo:[0,1] neg_hi:[0,1]
	v_add_f32_e32 v48, v159, v48
	v_pk_mul_f32 v[162:163], v[126:127], v[126:127]
	v_add_f32_e32 v48, v160, v48
	v_add_f32_e32 v48, v162, v48
	v_pk_add_f32 v[124:125], v[164:165], v[182:183] op_sel_hi:[1,0] neg_lo:[0,1] neg_hi:[0,1]
	v_add_f32_e32 v48, v161, v48
	v_pk_mul_f32 v[164:165], v[124:125], v[124:125]
	v_pk_add_f32 v[122:123], v[44:45], v[182:183] op_sel_hi:[1,0] neg_lo:[0,1] neg_hi:[0,1]
	v_add_f32_e32 v48, v163, v48
	v_pk_mul_f32 v[44:45], v[122:123], v[122:123]
	v_add_f32_e32 v48, v164, v48
	v_add_f32_e32 v44, v44, v48
	v_pk_add_f32 v[120:121], v[166:167], v[182:183] op_sel_hi:[1,0] neg_lo:[0,1] neg_hi:[0,1]
	v_add_f32_e32 v44, v165, v44
	v_pk_mul_f32 v[166:167], v[120:121], v[120:121]
	v_pk_add_f32 v[118:119], v[46:47], v[182:183] op_sel_hi:[1,0] neg_lo:[0,1] neg_hi:[0,1]
	v_add_f32_e32 v44, v45, v44
	v_pk_mul_f32 v[222:223], v[118:119], v[118:119]
	v_add_f32_e32 v44, v166, v44
	v_add_f32_e32 v44, v222, v44
	v_pk_add_f32 v[116:117], v[168:169], v[182:183] op_sel_hi:[1,0] neg_lo:[0,1] neg_hi:[0,1]
	v_add_f32_e32 v44, v167, v44
	v_pk_mul_f32 v[168:169], v[116:117], v[116:117]
	v_pk_add_f32 v[114:115], v[40:41], v[182:183] op_sel_hi:[1,0] neg_lo:[0,1] neg_hi:[0,1]
	v_add_f32_e32 v44, v223, v44
	v_pk_mul_f32 v[40:41], v[114:115], v[114:115]
	v_add_f32_e32 v44, v168, v44
	v_add_f32_e32 v40, v40, v44
	v_pk_add_f32 v[62:63], v[170:171], v[182:183] op_sel_hi:[1,0] neg_lo:[0,1] neg_hi:[0,1]
	v_add_f32_e32 v40, v169, v40
	v_pk_mul_f32 v[170:171], v[62:63], v[62:63]
	v_pk_add_f32 v[60:61], v[42:43], v[182:183] op_sel_hi:[1,0] neg_lo:[0,1] neg_hi:[0,1]
	v_add_f32_e32 v40, v41, v40
	v_pk_mul_f32 v[224:225], v[60:61], v[60:61]
	v_add_f32_e32 v40, v170, v40
	v_add_f32_e32 v40, v224, v40
	s_waitcnt vmcnt(1)
; __device__ __forceinline__ unsigned pk2(float lo, float hi) { return f2bf(lo) | (f2bf(hi) << 16); }
; __device__ __forceinline__ void p5_ln1(Frame& F, bool dummy) {
;     ...
;         const float mean = wave_sum(s) * (1.f / DM); float s2 = 0.f;
; #pragma unroll
;         for (int k = 0; k < 8; ++k)
; #pragma unroll
;             for (int e = 0; e < 8; ++e) { v[k][e] -= mean; s2 += v[k][e] * v[k][e]; }
;         const float rstd = rsqrtf(wave_sum(s2) * (1.f / DM) + LN_EPS);
; #pragma unroll
;         for (int k = 0; k < 8; ++k) { const int c = 8 * (lane + 64 * k);
;             const f32x4 g0 = *(const f32x4*)(F.ln1g + c), g1 = *(const f32x4*)(F.ln1g + c + 4), b0 = *(const f32x4*)(F.ln1b + c), b1 = *(const f32x4*)(F.ln1b + c + 4);
;             v4u w; w.x = pk2(v[k][0] * rstd * g0[0] + b0[0], v[k][1] * rstd * g0[1] + b0[1]); w.y = pk2(v[k][2] * rstd * g0[2] + b0[2], v[k][3] * rstd * g0[3] + b0[3]);
;             w.z = pk2(v[k][4] * rstd * g1[0] + b1[0], v[k][5] * rstd * g1[1] + b1[1]); w.w = pk2(v[k][6] * rstd * g1[2] + b1[2], v[k][7] * rstd * g1[3] + b1[3]);
;             *(v4u*)((dummy ? (bf16*)(F.ws + WS_E) + (size_t)(m & 4095) * DM : xr) + c) = w;
;             if (!dummy) { unsigned qb[8];
; #pragma unroll
;                 for (int e = 0; e < 8; ++e) { const float g = e < 4 ? g0[e] : g1[e - 4], bb = e < 4 ? b0[e] : b1[e - 4];
;                     qb[e] = (unsigned)(int)__builtin_rintf(fminf(fmaxf((v[k][e] * rstd * g + bb) * 24.f, -127.f), 127.f)) & 0xffu; }
;                 v2u o8; o8.x = qb[0] | (qb[2] << 8) | (qb[4] << 16) | (qb[6] << 24); o8.y = qb[1] | (qb[3] << 8) | (qb[5] << 16) | (qb[7] << 24);
;                 *(v2u*)(F.ws + WS_C + (size_t)m * DM + c) = o8; } }
	v_mov_b32_e32 v194, v56
	v_mov_b32_e32 v195, v58
	v_mov_b32_e32 v58, v57
	v_pk_add_f32 v[56:57], v[172:173], v[182:183] op_sel_hi:[1,0] neg_lo:[0,1] neg_hi:[0,1]
	v_add_f32_e32 v40, v171, v40
	v_mov_b32_e32 v192, v52
	v_mov_b32_e32 v193, v54
	v_mov_b32_e32 v54, v53
	v_pk_mul_f32 v[172:173], v[56:57], v[56:57]
	v_pk_add_f32 v[52:53], v[36:37], v[182:183] op_sel_hi:[1,0] neg_lo:[0,1] neg_hi:[0,1]
	v_add_f32_e32 v40, v225, v40
	v_pk_mul_f32 v[226:227], v[52:53], v[52:53]
	v_add_f32_e32 v40, v172, v40
	v_add_f32_e32 v40, v226, v40
	v_pk_add_f32 v[46:47], v[174:175], v[182:183] op_sel_hi:[1,0] neg_lo:[0,1] neg_hi:[0,1]
	v_add_f32_e32 v40, v173, v40
	v_pk_mul_f32 v[174:175], v[46:47], v[46:47]
	v_pk_add_f32 v[42:43], v[38:39], v[182:183] op_sel_hi:[1,0] neg_lo:[0,1] neg_hi:[0,1]
	v_add_f32_e32 v40, v227, v40
	v_pk_mul_f32 v[228:229], v[42:43], v[42:43]
	v_add_f32_e32 v40, v174, v40
	v_add_f32_e32 v40, v228, v40
	v_pk_add_f32 v[38:39], v[176:177], v[182:183] op_sel_hi:[1,0] neg_lo:[0,1] neg_hi:[0,1]
	v_add_f32_e32 v40, v175, v40
	v_pk_mul_f32 v[176:177], v[38:39], v[38:39]
	v_pk_add_f32 v[36:37], v[32:33], v[182:183] op_sel_hi:[1,0] neg_lo:[0,1] neg_hi:[0,1]
	v_add_f32_e32 v40, v229, v40
	v_pk_mul_f32 v[230:231], v[36:37], v[36:37]
	v_add_f32_e32 v40, v176, v40
	v_add_f32_e32 v40, v230, v40
	v_pk_add_f32 v[34:35], v[178:179], v[182:183] op_sel_hi:[1,0] neg_lo:[0,1] neg_hi:[0,1]
	v_add_f32_e32 v40, v177, v40
	v_pk_mul_f32 v[178:179], v[34:35], v[34:35]
	v_pk_add_f32 v[32:33], v[180:181], v[182:183] op_sel_hi:[1,0] neg_lo:[0,1] neg_hi:[0,1]
	v_add_f32_e32 v40, v231, v40
	v_pk_mul_f32 v[180:181], v[32:33], v[32:33]
	v_add_f32_e32 v40, v178, v40
	v_add_f32_e32 v40, v180, v40
	v_add_f32_e32 v40, v179, v40
	v_add_f32_e32 v40, v181, v40
	s_waitcnt vmcnt(0)
	v_mov_b32_e32 v44, v152
	v_mov_b32_e32 v45, v154
	v_add_f32_dpp v40, v40, v40 quad_perm:[1,0,3,2] row_mask:0xf bank_mask:0xf bound_ctrl:1
	v_mov_b32_e32 v154, v153
	v_mov_b32_e32 v205, v50
	v_add_f32_dpp v40, v40, v40 quad_perm:[2,3,0,1] row_mask:0xf bank_mask:0xf bound_ctrl:1
	v_mov_b32_e32 v50, v49
	v_lshl_add_u64 v[48:49], s[18:19], 0, v[108:109]
	v_add_f32_dpp v40, v40, v40 row_half_mirror row_mask:0xf bank_mask:0xf bound_ctrl:1
	v_lshl_add_u64 v[156:157], s[18:19], 0, v[92:93]
	v_lshl_add_u64 v[92:93], v[92:93], 0, s[8:9]
	v_add_f32_dpp v40, v40, v40 row_ror:8 row_mask:0xf bank_mask:0xf bound_ctrl:1
	ds_swizzle_b32 v41, v40 offset:swizzle(SWAP,16)
	v_lshl_add_u64 v[108:109], v[108:109], 0, s[6:7]
	s_waitcnt lgkmcnt(0)
	v_add_f32_e32 v40, v40, v41
	v_mov_b32_e32 v41, v40
	s_nop 1
	v_permlane32_swap_b32_e32 v40, v41
	v_add_f32_e32 v40, v40, v41
	v_fmamk_f32 v40, v40, 0x39800000, v150
	v_mul_f32_e32 v41, 0x4b800000, v40
	v_cmp_gt_f32_e32 vcc, s2, v40
	s_nop 1
	v_cndmask_b32_e32 v40, v40, v41, vcc
	v_rsq_f32_e32 v40, v40
	s_nop 0
	v_mul_f32_e32 v41, 0x45800000, v40
	v_cndmask_b32_e32 v40, v40, v41, vcc
	v_pk_mul_f32 v[152:153], v[184:185], v[40:41] op_sel_hi:[1,0]
	v_add_co_u32_e32 v48, vcc, s5, v48
	v_pk_fma_f32 v[158:159], v[192:193], v[152:153], v[194:195]
	v_pk_mul_f32 v[152:153], v[188:189], v[40:41] op_sel_hi:[1,0]
	v_addc_co_u32_e32 v49, vcc, 0, v49, vcc
	v_pk_fma_f32 v[54:55], v[54:55], v[152:153], v[58:59]
	v_pk_mul_f32 v[58:59], v[196:197], v[40:41] op_sel_hi:[1,0]
	v_bfe_u32 v153, v158, 16, 1
	v_pk_fma_f32 v[44:45], v[204:205], v[58:59], v[44:45]
	v_pk_mul_f32 v[58:59], v[200:201], v[40:41] op_sel_hi:[1,0]
	v_bfe_u32 v160, v45, 16, 1
	v_pk_fma_f32 v[50:51], v[50:51], v[58:59], v[154:155]
	v_bfe_u32 v154, v159, 16, 1
	v_bfe_u32 v155, v44, 16, 1
	v_bfe_u32 v58, v50, 16, 1
	v_add3_u32 v155, v44, v155, s3
	v_add3_u32 v154, v159, v154, s3
	v_add3_u32 v153, v158, v153, s3
	v_bfe_u32 v41, v51, 16, 1
	v_add3_u32 v58, v50, v58, s3
	v_add3_u32 v160, v45, v160, s3
	v_lshrrev_b32_e32 v161, 16, v153
	v_lshrrev_b32_e32 v153, 16, v154
	v_lshrrev_b32_e32 v154, 16, v155
	v_add3_u32 v41, v51, v41, s3
	v_lshrrev_b32_e32 v155, 16, v160
	v_and_or_b32 v154, v58, s1, v154
	v_mul_f32_e32 v58, 0x41c00000, v159
	v_mul_f32_e32 v50, 0x41c00000, v50
	v_bfe_u32 v59, v55, 16, 1
	v_and_or_b32 v155, v41, s1, v155
	v_mul_f32_e32 v41, 0x41c00000, v158
	v_med3_f32 v58, v58, s12, v151
	v_mul_f32_e32 v44, 0x41c00000, v44
	v_med3_f32 v50, v50, s12, v151
	v_mul_f32_e32 v45, 0x41c00000, v45
	v_bfe_u32 v152, v54, 16, 1
	v_add3_u32 v59, v55, v59, s3
	v_med3_f32 v41, v41, s12, v151
	v_rndne_f32_e32 v58, v58
	v_mul_f32_e32 v55, 0x41c00000, v55
	v_med3_f32 v44, v44, s12, v151
	v_rndne_f32_e32 v50, v50
	v_med3_f32 v45, v45, s12, v151
	v_add3_u32 v152, v54, v152, s3
	v_and_or_b32 v153, v59, s1, v153
	v_rndne_f32_e32 v41, v41
	v_mul_f32_e32 v54, 0x41c00000, v54
	v_cvt_i32_f32_e32 v58, v58
	v_med3_f32 v55, v55, s12, v151
	v_rndne_f32_e32 v44, v44
	v_cvt_i32_f32_sdwa v59, v50 dst_sel:WORD_1 dst_unused:UNUSED_PAD src0_sel:DWORD
	v_rndne_f32_e32 v45, v45
	v_mul_f32_e32 v50, 0x41c00000, v51
	v_cvt_i32_f32_e32 v41, v41
	v_med3_f32 v54, v54, s12, v151
	v_rndne_f32_e32 v55, v55
	v_cvt_i32_f32_sdwa v44, v44 dst_sel:WORD_1 dst_unused:UNUSED_PAD src0_sel:DWORD
	v_cvt_i32_f32_e32 v45, v45
	v_med3_f32 v50, v50, s12, v151
	v_rndne_f32_e32 v54, v54
	v_cvt_i32_f32_e32 v55, v55
	v_rndne_f32_e32 v50, v50
	v_cvt_i32_f32_e32 v54, v54
	v_cvt_i32_f32_e32 v51, v50
	v_lshlrev_b32_e32 v50, 8, v58
	v_and_b32_e32 v50, 0xff00, v50
	v_and_b32_e32 v44, 0xff0000, v44
	v_perm_b32 v41, v45, v41, s13
	v_or3_b32 v50, v41, v50, v44
	v_lshlrev_b32_e32 v41, 8, v55
	v_and_b32_e32 v41, 0xff00, v41
	v_and_b32_e32 v44, 0xff0000, v59
	v_perm_b32 v45, v51, v54, s13
	v_or3_b32 v51, v45, v41, v44
	v_add_co_u32_e32 v44, vcc, s14, v156
	v_and_or_b32 v152, v152, s1, v161
	s_nop 0
	v_addc_co_u32_e32 v45, vcc, 0, v157, vcc
	global_store_dwordx4 v[48:49], v[152:155], off
	global_store_dwordx2 v[44:45], v[50:51], off
	ds_read_b128 v[152:155], v252 offset:2048
	s_nop 0
	ds_read_b128 v[156:159], v252 offset:18432
	ds_read_b128 v[160:163], v252 offset:2064
	ds_read_b128 v[164:167], v252 offset:18448
	v_pk_mul_f32 v[50:51], v[148:149], v[40:41] op_sel_hi:[1,0]
	v_pk_mul_f32 v[142:143], v[142:143], v[40:41] op_sel_hi:[1,0]
	s_andn2_b64 vcc, exec, s[10:11]
	s_waitcnt lgkmcnt(3)
; __device__ __forceinline__ unsigned pk2(float lo, float hi) { return f2bf(lo) | (f2bf(hi) << 16); }
; __device__ __forceinline__ void p5_ln1(Frame& F, bool dummy) {
;     ...
;         for (int k = 0; k < 8; ++k) { const int c = 8 * (lane + 64 * k);
;             const f32x4 g0 = *(const f32x4*)(F.ln1g + c), g1 = *(const f32x4*)(F.ln1g + c + 4), b0 = *(const f32x4*)(F.ln1b + c), b1 = *(const f32x4*)(F.ln1b + c + 4);
;             v4u w; w.x = pk2(v[k][0] * rstd * g0[0] + b0[0], v[k][1] * rstd * g0[1] + b0[1]); w.y = pk2(v[k][2] * rstd * g0[2] + b0[2], v[k][3] * rstd * g0[3] + b0[3]);
;             w.z = pk2(v[k][4] * rstd * g1[0] + b1[0], v[k][5] * rstd * g1[1] + b1[1]); w.w = pk2(v[k][6] * rstd * g1[2] + b1[2], v[k][7] * rstd * g1[3] + b1[3]);
;             *(v4u*)((dummy ? (bf16*)(F.ws + WS_E) + (size_t)(m & 4095) * DM : xr) + c) = w;
;             if (!dummy) { unsigned qb[8];
; #pragma unroll
;                 for (int e = 0; e < 8; ++e) { const float g = e < 4 ? g0[e] : g1[e - 4], bb = e < 4 ? b0[e] : b1[e - 4];
;                     qb[e] = (unsigned)(int)__builtin_rintf(fminf(fmaxf((v[k][e] * rstd * g + bb) * 24.f, -127.f), 127.f)) & 0xffu; }
;                 v2u o8; o8.x = qb[0] | (qb[2] << 8) | (qb[4] << 16) | (qb[6] << 24); o8.y = qb[1] | (qb[3] << 8) | (qb[5] << 16) | (qb[7] << 24);
;                 *(v2u*)(F.ws + WS_C + (size_t)m * DM + c) = o8; } }
	v_mov_b32_e32 v54, v152
	v_mov_b32_e32 v55, v154
	s_waitcnt lgkmcnt(2)
	v_mov_b32_e32 v58, v156
	v_mov_b32_e32 v59, v158
	v_pk_fma_f32 v[50:51], v[54:55], v[50:51], v[58:59]
	v_pk_mul_f32 v[54:55], v[146:147], v[40:41] op_sel_hi:[1,0]
	v_pk_mul_f32 v[58:59], v[144:145], v[40:41] op_sel_hi:[1,0]
	s_waitcnt lgkmcnt(1)
	v_mov_b32_e32 v144, v160
	v_mov_b32_e32 v145, v162
	s_waitcnt lgkmcnt(0)
	v_mov_b32_e32 v146, v164
	v_mov_b32_e32 v147, v166
	v_mov_b32_e32 v154, v153
	v_mov_b32_e32 v158, v157
	v_pk_fma_f32 v[58:59], v[144:145], v[58:59], v[146:147]
	v_mov_b32_e32 v162, v161
	v_mov_b32_e32 v166, v165
	v_pk_fma_f32 v[54:55], v[154:155], v[54:55], v[158:159]
	v_pk_fma_f32 v[146:147], v[162:163], v[142:143], v[166:167]
	v_bfe_u32 v145, v51, 16, 1
	v_bfe_u32 v152, v59, 16, 1
	v_bfe_u32 v41, v147, 16, 1
	v_bfe_u32 v144, v54, 16, 1
	v_add3_u32 v152, v59, v152, s3
	v_add3_u32 v145, v51, v145, s3
	v_add3_u32 v148, v54, v144, s3
	v_add3_u32 v41, v147, v41, s3
	v_bfe_u32 v144, v50, 16, 1
	v_lshrrev_b32_e32 v154, 16, v145
	v_lshrrev_b32_e32 v145, 16, v152
	v_add3_u32 v144, v50, v144, s3
	v_and_or_b32 v145, v41, s1, v145
	v_mul_f32_e32 v41, 0x41c00000, v50
	v_mul_f32_e32 v50, 0x41c00000, v54
	v_med3_f32 v50, v50, s12, v151
	v_bfe_u32 v149, v58, 16, 1
	v_rndne_f32_e32 v50, v50
	v_bfe_u32 v142, v146, 16, 1
	v_bfe_u32 v143, v55, 16, 1
	v_add3_u32 v149, v58, v149, s3
	v_cvt_i32_f32_e32 v54, v50
	v_mul_f32_e32 v50, 0x41c00000, v51
	v_add3_u32 v143, v55, v143, s3
	v_add3_u32 v142, v146, v142, s3
	v_lshrrev_b32_e32 v153, 16, v144
	v_lshrrev_b32_e32 v144, 16, v149
	v_med3_f32 v50, v50, s12, v151
	v_mul_f32_e32 v51, 0x41c00000, v55
	v_mul_f32_e32 v55, 0x41c00000, v58
	v_mul_f32_e32 v59, 0x41c00000, v59
	v_and_or_b32 v144, v142, s1, v144
	v_and_or_b32 v143, v143, s1, v154
	v_and_or_b32 v142, v148, s1, v153
	v_med3_f32 v41, v41, s12, v151
	v_rndne_f32_e32 v50, v50
	v_med3_f32 v55, v55, s12, v151
	v_med3_f32 v59, v59, s12, v151
	global_store_dwordx4 v[48:49], v[142:145], off offset:1024
	v_rndne_f32_e32 v41, v41
	v_cvt_i32_f32_e32 v50, v50
	v_med3_f32 v51, v51, s12, v151
	v_rndne_f32_e32 v55, v55
	v_mul_f32_e32 v58, 0x41c00000, v146
	v_rndne_f32_e32 v59, v59
	v_mul_f32_e32 v142, 0x41c00000, v147
	v_cvt_i32_f32_e32 v41, v41
	v_rndne_f32_e32 v51, v51
	v_cvt_i32_f32_sdwa v55, v55 dst_sel:WORD_1 dst_unused:UNUSED_PAD src0_sel:DWORD
	v_med3_f32 v58, v58, s12, v151
	v_cvt_i32_f32_e32 v59, v59
	v_med3_f32 v142, v142, s12, v151
	v_cvt_i32_f32_e32 v51, v51
	v_rndne_f32_e32 v58, v58
	v_rndne_f32_e32 v142, v142
	v_cvt_i32_f32_sdwa v58, v58 dst_sel:WORD_1 dst_unused:UNUSED_PAD src0_sel:DWORD
	v_cvt_i32_f32_e32 v142, v142
	v_lshlrev_b32_e32 v50, 8, v50
	v_and_b32_e32 v50, 0xff00, v50
	v_and_b32_e32 v55, 0xff0000, v55
	v_perm_b32 v41, v59, v41, s13
	v_or3_b32 v50, v41, v50, v55
	v_lshlrev_b32_e32 v41, 8, v51
	v_and_b32_e32 v41, 0xff00, v41
	v_and_b32_e32 v51, 0xff0000, v58
	v_perm_b32 v54, v142, v54, s13
	v_or3_b32 v51, v54, v41, v51
	global_store_dwordx2 v[44:45], v[50:51], off offset:512
	ds_read_b128 v[142:145], v252 offset:4096
	ds_read_b128 v[146:149], v252 offset:20480
	ds_read_b128 v[152:155], v252 offset:4112
	ds_read_b128 v[156:159], v252 offset:20496
	v_pk_mul_f32 v[50:51], v[140:141], v[40:41] op_sel_hi:[1,0]
	v_pk_mul_f32 v[134:135], v[134:135], v[40:41] op_sel_hi:[1,0]
	s_waitcnt lgkmcnt(3)
	v_mov_b32_e32 v54, v142
	v_mov_b32_e32 v55, v144
	s_waitcnt lgkmcnt(2)
	v_mov_b32_e32 v58, v146
	v_mov_b32_e32 v59, v148
	v_pk_fma_f32 v[50:51], v[50:51], v[54:55], v[58:59]
	v_pk_mul_f32 v[54:55], v[138:139], v[40:41] op_sel_hi:[1,0]
	v_pk_mul_f32 v[58:59], v[136:137], v[40:41] op_sel_hi:[1,0]
	s_waitcnt lgkmcnt(1)
	v_mov_b32_e32 v136, v152
	v_mov_b32_e32 v137, v154
	s_waitcnt lgkmcnt(0)
	v_mov_b32_e32 v138, v156
	v_mov_b32_e32 v139, v158
	v_mov_b32_e32 v144, v143
	v_mov_b32_e32 v148, v147
	v_pk_fma_f32 v[58:59], v[58:59], v[136:137], v[138:139]
	v_mov_b32_e32 v154, v153
	v_mov_b32_e32 v158, v157
	v_pk_fma_f32 v[54:55], v[54:55], v[144:145], v[148:149]
	v_pk_fma_f32 v[138:139], v[134:135], v[154:155], v[158:159]
	v_bfe_u32 v137, v51, 16, 1
	v_bfe_u32 v142, v59, 16, 1
	v_bfe_u32 v41, v139, 16, 1
	v_bfe_u32 v136, v54, 16, 1
	v_add3_u32 v142, v59, v142, s3
	v_add3_u32 v137, v51, v137, s3
	v_add3_u32 v140, v54, v136, s3
	v_add3_u32 v41, v139, v41, s3
	v_bfe_u32 v136, v50, 16, 1
	v_lshrrev_b32_e32 v144, 16, v137
	v_lshrrev_b32_e32 v137, 16, v142
	v_add3_u32 v136, v50, v136, s3
	v_and_or_b32 v137, v41, s1, v137
	v_mul_f32_e32 v41, 0x41c00000, v50
	v_mul_f32_e32 v50, 0x41c00000, v54
	v_med3_f32 v50, v50, s12, v151
	v_rndne_f32_e32 v50, v50
	v_bfe_u32 v135, v55, 16, 1
	v_bfe_u32 v141, v58, 16, 1
	v_cvt_i32_f32_e32 v54, v50
	v_mul_f32_e32 v50, 0x41c00000, v51
	v_bfe_u32 v134, v138, 16, 1
	v_add3_u32 v135, v55, v135, s3
	v_add3_u32 v141, v58, v141, s3
	v_med3_f32 v50, v50, s12, v151
	v_mul_f32_e32 v51, 0x41c00000, v55
	v_mul_f32_e32 v55, 0x41c00000, v58
	v_add3_u32 v134, v138, v134, s3
	v_lshrrev_b32_e32 v143, 16, v136
	v_lshrrev_b32_e32 v136, 16, v141
	v_med3_f32 v41, v41, s12, v151
	v_rndne_f32_e32 v50, v50
	v_med3_f32 v55, v55, s12, v151
	v_mul_f32_e32 v59, 0x41c00000, v59
	v_and_or_b32 v136, v134, s1, v136
	v_and_or_b32 v135, v135, s1, v144
	v_and_or_b32 v134, v140, s1, v143
	v_rndne_f32_e32 v41, v41
	v_cvt_i32_f32_e32 v50, v50
	v_med3_f32 v51, v51, s12, v151
	v_rndne_f32_e32 v55, v55
	v_mul_f32_e32 v58, 0x41c00000, v138
	v_med3_f32 v59, v59, s12, v151
	global_store_dwordx4 v[48:49], v[134:137], off offset:2048
	v_cvt_i32_f32_e32 v41, v41
	v_rndne_f32_e32 v51, v51
	v_cvt_i32_f32_sdwa v55, v55 dst_sel:WORD_1 dst_unused:UNUSED_PAD src0_sel:DWORD
	v_med3_f32 v58, v58, s12, v151
	v_rndne_f32_e32 v59, v59
	v_mul_f32_e32 v134, 0x41c00000, v139
	v_cvt_i32_f32_e32 v51, v51
	v_rndne_f32_e32 v58, v58
	v_cvt_i32_f32_sdwa v59, v59 dst_sel:BYTE_3 dst_unused:UNUSED_PAD src0_sel:DWORD
	v_med3_f32 v134, v134, s12, v151
	v_cvt_i32_f32_sdwa v58, v58 dst_sel:WORD_1 dst_unused:UNUSED_PAD src0_sel:DWORD
	v_rndne_f32_e32 v134, v134
	v_cvt_i32_f32_sdwa v134, v134 dst_sel:BYTE_3 dst_unused:UNUSED_PAD src0_sel:DWORD
	v_lshlrev_b32_e32 v50, 8, v50
	v_and_b32_e32 v55, 0xff0000, v55
	v_perm_b32 v41, v50, v41, s15
	v_or3_b32 v50, v41, v59, v55
	v_lshlrev_b32_e32 v41, 8, v51
	v_and_b32_e32 v51, 0xff0000, v58
	v_perm_b32 v41, v41, v54, s15
	v_or3_b32 v51, v41, v134, v51
	global_store_dwordx2 v[44:45], v[50:51], off offset:1024
	ds_read_b128 v[134:137], v252 offset:6144
	ds_read_b128 v[138:141], v252 offset:22528
	ds_read_b128 v[142:145], v252 offset:6160
	ds_read_b128 v[146:149], v252 offset:22544
	v_pk_mul_f32 v[50:51], v[132:133], v[40:41] op_sel_hi:[1,0]
	v_pk_mul_f32 v[126:127], v[126:127], v[40:41] op_sel_hi:[1,0]
	s_waitcnt lgkmcnt(3)
; __device__ __forceinline__ unsigned pk2(float lo, float hi) { return f2bf(lo) | (f2bf(hi) << 16); }
; __device__ __forceinline__ void p5_ln1(Frame& F, bool dummy) {
;     ...
;         for (int k = 0; k < 8; ++k) { const int c = 8 * (lane + 64 * k);
;             const f32x4 g0 = *(const f32x4*)(F.ln1g + c), g1 = *(const f32x4*)(F.ln1g + c + 4), b0 = *(const f32x4*)(F.ln1b + c), b1 = *(const f32x4*)(F.ln1b + c + 4);
;             v4u w; w.x = pk2(v[k][0] * rstd * g0[0] + b0[0], v[k][1] * rstd * g0[1] + b0[1]); w.y = pk2(v[k][2] * rstd * g0[2] + b0[2], v[k][3] * rstd * g0[3] + b0[3]);
;             w.z = pk2(v[k][4] * rstd * g1[0] + b1[0], v[k][5] * rstd * g1[1] + b1[1]); w.w = pk2(v[k][6] * rstd * g1[2] + b1[2], v[k][7] * rstd * g1[3] + b1[3]);
;             *(v4u*)((dummy ? (bf16*)(F.ws + WS_E) + (size_t)(m & 4095) * DM : xr) + c) = w;
;             if (!dummy) { unsigned qb[8];
; #pragma unroll
;                 for (int e = 0; e < 8; ++e) { const float g = e < 4 ? g0[e] : g1[e - 4], bb = e < 4 ? b0[e] : b1[e - 4];
;                     qb[e] = (unsigned)(int)__builtin_rintf(fminf(fmaxf((v[k][e] * rstd * g + bb) * 24.f, -127.f), 127.f)) & 0xffu; }
;                 v2u o8; o8.x = qb[0] | (qb[2] << 8) | (qb[4] << 16) | (qb[6] << 24); o8.y = qb[1] | (qb[3] << 8) | (qb[5] << 16) | (qb[7] << 24);
;                 *(v2u*)(F.ws + WS_C + (size_t)m * DM + c) = o8; } }
	v_mov_b32_e32 v54, v134
	v_mov_b32_e32 v55, v136
	s_waitcnt lgkmcnt(2)
	v_mov_b32_e32 v58, v138
	v_mov_b32_e32 v59, v140
	v_pk_fma_f32 v[50:51], v[50:51], v[54:55], v[58:59]
	v_pk_mul_f32 v[54:55], v[130:131], v[40:41] op_sel_hi:[1,0]
	v_mov_b32_e32 v136, v135
	v_mov_b32_e32 v140, v139
	v_pk_fma_f32 v[54:55], v[54:55], v[136:137], v[140:141]
	v_pk_mul_f32 v[58:59], v[128:129], v[40:41] op_sel_hi:[1,0]
	s_waitcnt lgkmcnt(1)
	v_mov_b32_e32 v128, v142
	v_mov_b32_e32 v129, v144
	s_waitcnt lgkmcnt(0)
	v_mov_b32_e32 v130, v146
	v_mov_b32_e32 v131, v148
	v_pk_fma_f32 v[58:59], v[58:59], v[128:129], v[130:131]
	v_mov_b32_e32 v144, v143
	v_mov_b32_e32 v148, v147
	v_bfe_u32 v128, v54, 16, 1
	v_pk_fma_f32 v[130:131], v[126:127], v[144:145], v[148:149]
	v_add3_u32 v132, v54, v128, s3
	v_bfe_u32 v128, v50, 16, 1
	v_bfe_u32 v129, v51, 16, 1
	v_bfe_u32 v133, v58, 16, 1
	v_bfe_u32 v134, v59, 16, 1
	v_bfe_u32 v41, v131, 16, 1
	v_bfe_u32 v126, v130, 16, 1
	v_bfe_u32 v127, v55, 16, 1
	v_add3_u32 v134, v59, v134, s3
	v_add3_u32 v133, v58, v133, s3
	v_add3_u32 v129, v51, v129, s3
	v_add3_u32 v128, v50, v128, s3
	v_add3_u32 v127, v55, v127, s3
	v_add3_u32 v126, v130, v126, s3
	v_add3_u32 v41, v131, v41, s3
	v_lshrrev_b32_e32 v135, 16, v128
	v_lshrrev_b32_e32 v136, 16, v129
	v_lshrrev_b32_e32 v128, 16, v133
	v_lshrrev_b32_e32 v129, 16, v134
	v_and_or_b32 v129, v41, s1, v129
	v_and_or_b32 v128, v126, s1, v128
	v_and_or_b32 v127, v127, s1, v136
	v_and_or_b32 v126, v132, s1, v135
	global_store_dwordx4 v[48:49], v[126:129], off offset:3072
	v_mul_f32_e32 v48, 0x41c00000, v54
	v_med3_f32 v48, v48, s12, v151
	v_rndne_f32_e32 v48, v48
	v_cvt_i32_f32_e32 v49, v48
	v_mul_f32_e32 v48, 0x41c00000, v51
	v_mul_f32_e32 v41, 0x41c00000, v50
	v_med3_f32 v48, v48, s12, v151
	v_mul_f32_e32 v51, 0x41c00000, v58
	v_med3_f32 v41, v41, s12, v151
	v_rndne_f32_e32 v48, v48
	v_mul_f32_e32 v50, 0x41c00000, v55
	v_med3_f32 v51, v51, s12, v151
	v_mul_f32_e32 v55, 0x41c00000, v59
	v_rndne_f32_e32 v41, v41
	v_cvt_i32_f32_e32 v48, v48
	v_med3_f32 v50, v50, s12, v151
	v_rndne_f32_e32 v51, v51
	v_mul_f32_e32 v54, 0x41c00000, v130
	v_med3_f32 v55, v55, s12, v151
	v_cvt_i32_f32_e32 v41, v41
	v_rndne_f32_e32 v50, v50
	v_cvt_i32_f32_sdwa v51, v51 dst_sel:WORD_1 dst_unused:UNUSED_PAD src0_sel:DWORD
	v_med3_f32 v54, v54, s12, v151
	v_rndne_f32_e32 v55, v55
	v_mul_f32_e32 v58, 0x41c00000, v131
	v_cvt_i32_f32_e32 v50, v50
	v_rndne_f32_e32 v54, v54
	v_cvt_i32_f32_sdwa v55, v55 dst_sel:BYTE_3 dst_unused:UNUSED_PAD src0_sel:DWORD
	v_med3_f32 v58, v58, s12, v151
	v_cvt_i32_f32_sdwa v54, v54 dst_sel:WORD_1 dst_unused:UNUSED_PAD src0_sel:DWORD
	v_rndne_f32_e32 v58, v58
	v_cvt_i32_f32_sdwa v58, v58 dst_sel:BYTE_3 dst_unused:UNUSED_PAD src0_sel:DWORD
	v_lshlrev_b32_e32 v48, 8, v48
	v_and_b32_e32 v51, 0xff0000, v51
	v_perm_b32 v41, v48, v41, s15
	v_or3_b32 v48, v41, v55, v51
	v_lshlrev_b32_e32 v41, 8, v50
	v_and_b32_e32 v50, 0xff0000, v54
	v_perm_b32 v41, v41, v49, s15
	v_or3_b32 v49, v41, v58, v50
	global_store_dwordx2 v[44:45], v[48:49], off offset:1536
	ds_read_b128 v[48:51], v252 offset:8192
	s_nop 0
	ds_read_b128 v[126:129], v252 offset:24576
	ds_read_b128 v[130:133], v252 offset:8208
	ds_read_b128 v[134:137], v252 offset:24592
	v_pk_mul_f32 v[58:59], v[124:125], v[40:41] op_sel_hi:[1,0]
	v_pk_mul_f32 v[122:123], v[122:123], v[40:41] op_sel_hi:[1,0]
	v_lshl_add_u64 v[54:55], s[18:19], 0, v[110:111]
	v_lshl_add_u64 v[110:111], v[110:111], 0, s[6:7]
	s_waitcnt lgkmcnt(3)
	v_mov_b32_e32 v125, v50
	s_waitcnt lgkmcnt(2)
	v_mov_b32_e32 v139, v128
	v_mov_b32_e32 v50, v49
	v_mov_b32_e32 v128, v127
	v_mov_b32_e32 v124, v48
	v_mov_b32_e32 v138, v126
	v_pk_fma_f32 v[122:123], v[122:123], v[50:51], v[128:129]
	v_pk_mul_f32 v[48:49], v[120:121], v[40:41] op_sel_hi:[1,0]
	s_waitcnt lgkmcnt(1)
	v_mov_b32_e32 v50, v130
	v_mov_b32_e32 v51, v132
	s_waitcnt lgkmcnt(0)
	v_mov_b32_e32 v120, v134
	v_mov_b32_e32 v121, v136
	v_pk_fma_f32 v[58:59], v[58:59], v[124:125], v[138:139]
	v_pk_fma_f32 v[120:121], v[48:49], v[50:51], v[120:121]
	v_pk_mul_f32 v[48:49], v[118:119], v[40:41] op_sel_hi:[1,0]
	v_mov_b32_e32 v132, v131
	v_mov_b32_e32 v136, v135
	v_bfe_u32 v50, v122, 16, 1
	v_pk_fma_f32 v[118:119], v[48:49], v[132:133], v[136:137]
	v_add3_u32 v124, v122, v50, s3
	v_bfe_u32 v50, v58, 16, 1
	v_bfe_u32 v51, v59, 16, 1
	v_bfe_u32 v125, v120, 16, 1
	v_bfe_u32 v126, v121, 16, 1
	v_bfe_u32 v41, v119, 16, 1
	v_bfe_u32 v48, v118, 16, 1
	v_bfe_u32 v49, v123, 16, 1
	v_add3_u32 v126, v121, v126, s3
	v_add3_u32 v125, v120, v125, s3
	v_add3_u32 v51, v59, v51, s3
	v_add3_u32 v50, v58, v50, s3
	v_add3_u32 v49, v123, v49, s3
	v_add3_u32 v48, v118, v48, s3
	v_add3_u32 v41, v119, v41, s3
	v_lshrrev_b32_e32 v127, 16, v50
	v_lshrrev_b32_e32 v128, 16, v51
	v_lshrrev_b32_e32 v50, 16, v125
	v_lshrrev_b32_e32 v51, 16, v126
	v_and_or_b32 v51, v41, s1, v51
	v_and_or_b32 v50, v48, s1, v50
	v_and_or_b32 v49, v49, s1, v128
	v_and_or_b32 v48, v124, s1, v127
	global_store_dwordx4 v[54:55], v[48:51], off
	v_mul_f32_e32 v41, 0x41c00000, v58
	v_med3_f32 v41, v41, s12, v151
	v_mul_f32_e32 v48, 0x41c00000, v122
	v_med3_f32 v48, v48, s12, v151
	v_rndne_f32_e32 v48, v48
	v_cvt_i32_f32_e32 v49, v48
	v_mul_f32_e32 v48, 0x41c00000, v59
	v_med3_f32 v48, v48, s12, v151
	v_mul_f32_e32 v51, 0x41c00000, v120
	v_rndne_f32_e32 v48, v48
	v_mul_f32_e32 v50, 0x41c00000, v123
	v_med3_f32 v51, v51, s12, v151
	v_mul_f32_e32 v55, 0x41c00000, v121
	v_rndne_f32_e32 v41, v41
	v_cvt_i32_f32_e32 v48, v48
	v_med3_f32 v50, v50, s12, v151
	v_rndne_f32_e32 v51, v51
	v_mul_f32_e32 v54, 0x41c00000, v118
	v_med3_f32 v55, v55, s12, v151
	v_cvt_i32_f32_e32 v41, v41
	v_rndne_f32_e32 v50, v50
	v_cvt_i32_f32_sdwa v51, v51 dst_sel:WORD_1 dst_unused:UNUSED_PAD src0_sel:DWORD
	v_med3_f32 v54, v54, s12, v151
	v_rndne_f32_e32 v55, v55
	v_mul_f32_e32 v58, 0x41c00000, v119
	v_cvt_i32_f32_e32 v50, v50
	v_rndne_f32_e32 v54, v54
	v_cvt_i32_f32_sdwa v55, v55 dst_sel:BYTE_3 dst_unused:UNUSED_PAD src0_sel:DWORD
	v_med3_f32 v58, v58, s12, v151
	v_cvt_i32_f32_sdwa v54, v54 dst_sel:WORD_1 dst_unused:UNUSED_PAD src0_sel:DWORD
	v_rndne_f32_e32 v58, v58
	v_cvt_i32_f32_sdwa v58, v58 dst_sel:BYTE_3 dst_unused:UNUSED_PAD src0_sel:DWORD
	v_lshlrev_b32_e32 v48, 8, v48
	v_and_b32_e32 v51, 0xff0000, v51
	v_perm_b32 v41, v48, v41, s15
	v_or3_b32 v48, v41, v55, v51
	v_lshlrev_b32_e32 v41, 8, v50
	v_and_b32_e32 v50, 0xff0000, v54
	v_perm_b32 v41, v41, v49, s15
	v_or3_b32 v49, v41, v58, v50
	global_store_dwordx2 v[44:45], v[48:49], off offset:2048
	ds_read_b128 v[48:51], v252 offset:10240
	s_nop 0
	ds_read_b128 v[118:121], v252 offset:26624
	ds_read_b128 v[122:125], v252 offset:10256
	ds_read_b128 v[126:129], v252 offset:26640
	v_pk_mul_f32 v[58:59], v[116:117], v[40:41] op_sel_hi:[1,0]
	v_pk_mul_f32 v[114:115], v[114:115], v[40:41] op_sel_hi:[1,0]
	v_lshl_add_u64 v[54:55], s[18:19], 0, v[112:113]
	v_lshl_add_u64 v[112:113], v[112:113], 0, s[6:7]
	s_waitcnt lgkmcnt(3)
; __device__ __forceinline__ unsigned pk2(float lo, float hi) { return f2bf(lo) | (f2bf(hi) << 16); }
; __device__ __forceinline__ void p5_ln1(Frame& F, bool dummy) {
;     ...
;         for (int k = 0; k < 8; ++k) { const int c = 8 * (lane + 64 * k);
;             const f32x4 g0 = *(const f32x4*)(F.ln1g + c), g1 = *(const f32x4*)(F.ln1g + c + 4), b0 = *(const f32x4*)(F.ln1b + c), b1 = *(const f32x4*)(F.ln1b + c + 4);
;             v4u w; w.x = pk2(v[k][0] * rstd * g0[0] + b0[0], v[k][1] * rstd * g0[1] + b0[1]); w.y = pk2(v[k][2] * rstd * g0[2] + b0[2], v[k][3] * rstd * g0[3] + b0[3]);
;             w.z = pk2(v[k][4] * rstd * g1[0] + b1[0], v[k][5] * rstd * g1[1] + b1[1]); w.w = pk2(v[k][6] * rstd * g1[2] + b1[2], v[k][7] * rstd * g1[3] + b1[3]);
;             *(v4u*)((dummy ? (bf16*)(F.ws + WS_E) + (size_t)(m & 4095) * DM : xr) + c) = w;
;             if (!dummy) { unsigned qb[8];
; #pragma unroll
;                 for (int e = 0; e < 8; ++e) { const float g = e < 4 ? g0[e] : g1[e - 4], bb = e < 4 ? b0[e] : b1[e - 4];
;                     qb[e] = (unsigned)(int)__builtin_rintf(fminf(fmaxf((v[k][e] * rstd * g + bb) * 24.f, -127.f), 127.f)) & 0xffu; }
;                 v2u o8; o8.x = qb[0] | (qb[2] << 8) | (qb[4] << 16) | (qb[6] << 24); o8.y = qb[1] | (qb[3] << 8) | (qb[5] << 16) | (qb[7] << 24);
;                 *(v2u*)(F.ws + WS_C + (size_t)m * DM + c) = o8; } }
	v_mov_b32_e32 v117, v50
	s_waitcnt lgkmcnt(2)
	v_mov_b32_e32 v131, v120
	v_mov_b32_e32 v50, v49
	v_mov_b32_e32 v120, v119
	v_mov_b32_e32 v116, v48
	v_mov_b32_e32 v130, v118
	v_pk_fma_f32 v[114:115], v[114:115], v[50:51], v[120:121]
	v_pk_mul_f32 v[48:49], v[62:63], v[40:41] op_sel_hi:[1,0]
	s_waitcnt lgkmcnt(1)
	v_mov_b32_e32 v50, v122
	v_mov_b32_e32 v51, v124
	s_waitcnt lgkmcnt(0)
	v_mov_b32_e32 v62, v126
	v_mov_b32_e32 v63, v128
	v_pk_fma_f32 v[58:59], v[58:59], v[116:117], v[130:131]
	v_pk_fma_f32 v[62:63], v[48:49], v[50:51], v[62:63]
	v_pk_mul_f32 v[48:49], v[60:61], v[40:41] op_sel_hi:[1,0]
	v_mov_b32_e32 v124, v123
	v_mov_b32_e32 v128, v127
	v_bfe_u32 v50, v114, 16, 1
	v_pk_fma_f32 v[60:61], v[48:49], v[124:125], v[128:129]
	v_add3_u32 v116, v114, v50, s3
	v_bfe_u32 v50, v58, 16, 1
	v_bfe_u32 v51, v59, 16, 1
	v_bfe_u32 v117, v62, 16, 1
	v_bfe_u32 v118, v63, 16, 1
	v_bfe_u32 v41, v61, 16, 1
	v_bfe_u32 v48, v60, 16, 1
	v_bfe_u32 v49, v115, 16, 1
	v_add3_u32 v118, v63, v118, s3
	v_add3_u32 v117, v62, v117, s3
	v_add3_u32 v51, v59, v51, s3
	v_add3_u32 v50, v58, v50, s3
	v_add3_u32 v49, v115, v49, s3
	v_add3_u32 v48, v60, v48, s3
	v_add3_u32 v41, v61, v41, s3
	v_lshrrev_b32_e32 v119, 16, v50
	v_lshrrev_b32_e32 v120, 16, v51
	v_lshrrev_b32_e32 v50, 16, v117
	v_lshrrev_b32_e32 v51, 16, v118
	v_and_or_b32 v51, v41, s1, v51
	v_and_or_b32 v50, v48, s1, v50
	v_and_or_b32 v49, v49, s1, v120
	v_and_or_b32 v48, v116, s1, v119
	global_store_dwordx4 v[54:55], v[48:51], off
	v_mul_f32_e32 v41, 0x41c00000, v58
	v_med3_f32 v41, v41, s12, v151
	v_mul_f32_e32 v48, 0x41c00000, v114
	v_med3_f32 v48, v48, s12, v151
	v_rndne_f32_e32 v48, v48
	v_cvt_i32_f32_e32 v49, v48
	v_mul_f32_e32 v48, 0x41c00000, v59
	v_med3_f32 v48, v48, s12, v151
	v_mul_f32_e32 v51, 0x41c00000, v62
	v_rndne_f32_e32 v48, v48
	v_mul_f32_e32 v50, 0x41c00000, v115
	v_med3_f32 v51, v51, s12, v151
	v_mul_f32_e32 v55, 0x41c00000, v63
	v_rndne_f32_e32 v41, v41
	v_cvt_i32_f32_e32 v48, v48
	v_med3_f32 v50, v50, s12, v151
	v_rndne_f32_e32 v51, v51
	v_mul_f32_e32 v54, 0x41c00000, v60
	v_med3_f32 v55, v55, s12, v151
	v_cvt_i32_f32_e32 v41, v41
	v_rndne_f32_e32 v50, v50
	v_cvt_i32_f32_sdwa v51, v51 dst_sel:WORD_1 dst_unused:UNUSED_PAD src0_sel:DWORD
	v_med3_f32 v54, v54, s12, v151
	v_rndne_f32_e32 v55, v55
	v_mul_f32_e32 v58, 0x41c00000, v61
	v_cvt_i32_f32_e32 v50, v50
	v_rndne_f32_e32 v54, v54
	v_cvt_i32_f32_sdwa v55, v55 dst_sel:BYTE_3 dst_unused:UNUSED_PAD src0_sel:DWORD
	v_med3_f32 v58, v58, s12, v151
	v_cvt_i32_f32_sdwa v54, v54 dst_sel:WORD_1 dst_unused:UNUSED_PAD src0_sel:DWORD
	v_rndne_f32_e32 v58, v58
	v_cvt_i32_f32_sdwa v58, v58 dst_sel:BYTE_3 dst_unused:UNUSED_PAD src0_sel:DWORD
	v_lshlrev_b32_e32 v48, 8, v48
	v_and_b32_e32 v51, 0xff0000, v51
	v_perm_b32 v41, v48, v41, s15
	v_or3_b32 v48, v41, v55, v51
	v_lshlrev_b32_e32 v41, 8, v50
	v_and_b32_e32 v50, 0xff0000, v54
	v_perm_b32 v41, v41, v49, s15
	v_or3_b32 v49, v41, v58, v50
	global_store_dwordx2 v[44:45], v[48:49], off offset:2560
	ds_read_b128 v[48:51], v252 offset:12288
	s_nop 0
	ds_read_b128 v[58:61], v252 offset:28672
	ds_read_b128 v[114:117], v252 offset:12304
	ds_read_b128 v[118:121], v252 offset:28688
	v_pk_mul_f32 v[52:53], v[52:53], v[40:41] op_sel_hi:[1,0]
	v_pk_mul_f32 v[56:57], v[56:57], v[40:41] op_sel_hi:[1,0]
	v_pk_mul_f32 v[46:47], v[46:47], v[40:41] op_sel_hi:[1,0]
	v_pk_mul_f32 v[42:43], v[42:43], v[40:41] op_sel_hi:[1,0]
	v_lshl_add_u64 v[54:55], s[18:19], 0, v[98:99]
	v_lshl_add_u64 v[98:99], v[98:99], 0, s[6:7]
	s_waitcnt lgkmcnt(3)
	v_mov_b32_e32 v63, v50
	s_waitcnt lgkmcnt(2)
	v_mov_b32_e32 v123, v60
	v_mov_b32_e32 v50, v49
	v_mov_b32_e32 v60, v59
	v_mov_b32_e32 v62, v48
	v_mov_b32_e32 v122, v58
	v_pk_fma_f32 v[50:51], v[52:53], v[50:51], v[60:61]
	s_waitcnt lgkmcnt(1)
	v_mov_b32_e32 v48, v114
	v_mov_b32_e32 v49, v116
	s_waitcnt lgkmcnt(0)
; __device__ __forceinline__ unsigned pk2(float lo, float hi) { return f2bf(lo) | (f2bf(hi) << 16); }
; __device__ __forceinline__ void p5_ln1(Frame& F, bool dummy) {
;     ...
;         for (int k = 0; k < 8; ++k) { const int c = 8 * (lane + 64 * k);
;             const f32x4 g0 = *(const f32x4*)(F.ln1g + c), g1 = *(const f32x4*)(F.ln1g + c + 4), b0 = *(const f32x4*)(F.ln1b + c), b1 = *(const f32x4*)(F.ln1b + c + 4);
;             v4u w; w.x = pk2(v[k][0] * rstd * g0[0] + b0[0], v[k][1] * rstd * g0[1] + b0[1]); w.y = pk2(v[k][2] * rstd * g0[2] + b0[2], v[k][3] * rstd * g0[3] + b0[3]);
;             w.z = pk2(v[k][4] * rstd * g1[0] + b1[0], v[k][5] * rstd * g1[1] + b1[1]); w.w = pk2(v[k][6] * rstd * g1[2] + b1[2], v[k][7] * rstd * g1[3] + b1[3]);
;             *(v4u*)((dummy ? (bf16*)(F.ws + WS_E) + (size_t)(m & 4095) * DM : xr) + c) = w;
;             if (!dummy) { unsigned qb[8];
; #pragma unroll
;                 for (int e = 0; e < 8; ++e) { const float g = e < 4 ? g0[e] : g1[e - 4], bb = e < 4 ? b0[e] : b1[e - 4];
;                     qb[e] = (unsigned)(int)__builtin_rintf(fminf(fmaxf((v[k][e] * rstd * g + bb) * 24.f, -127.f), 127.f)) & 0xffu; }
;                 v2u o8; o8.x = qb[0] | (qb[2] << 8) | (qb[4] << 16) | (qb[6] << 24); o8.y = qb[1] | (qb[3] << 8) | (qb[5] << 16) | (qb[7] << 24);
;                 *(v2u*)(F.ws + WS_C + (size_t)m * DM + c) = o8; } }
;     }
	v_mov_b32_e32 v52, v118
	v_mov_b32_e32 v53, v120
	v_pk_fma_f32 v[56:57], v[56:57], v[62:63], v[122:123]
	v_pk_fma_f32 v[52:53], v[46:47], v[48:49], v[52:53]
	v_mov_b32_e32 v116, v115
	v_mov_b32_e32 v120, v119
	v_bfe_u32 v48, v50, 16, 1
	v_pk_fma_f32 v[42:43], v[42:43], v[116:117], v[120:121]
	v_add3_u32 v58, v50, v48, s3
	v_bfe_u32 v48, v56, 16, 1
	v_bfe_u32 v49, v57, 16, 1
	v_bfe_u32 v59, v52, 16, 1
	v_bfe_u32 v60, v53, 16, 1
	v_bfe_u32 v41, v43, 16, 1
	v_bfe_u32 v46, v42, 16, 1
	v_bfe_u32 v47, v51, 16, 1
	v_add3_u32 v60, v53, v60, s3
	v_add3_u32 v59, v52, v59, s3
	v_add3_u32 v49, v57, v49, s3
	v_add3_u32 v48, v56, v48, s3
	v_add3_u32 v47, v51, v47, s3
	v_add3_u32 v46, v42, v46, s3
	v_add3_u32 v41, v43, v41, s3
	v_lshrrev_b32_e32 v61, 16, v48
	v_lshrrev_b32_e32 v62, 16, v49
	v_lshrrev_b32_e32 v48, 16, v59
	v_lshrrev_b32_e32 v49, 16, v60
	v_and_or_b32 v49, v41, s1, v49
	v_and_or_b32 v48, v46, s1, v48
	v_and_or_b32 v47, v47, s1, v62
	v_and_or_b32 v46, v58, s1, v61
	v_mul_f32_e32 v42, 0x41c00000, v42
	global_store_dwordx4 v[54:55], v[46:49], off
	v_med3_f32 v42, v42, s12, v151
	v_mul_f32_e32 v41, 0x41c00000, v56
	v_mul_f32_e32 v47, 0x41c00000, v57
	v_med3_f32 v47, v47, s12, v151
	v_mul_f32_e32 v49, 0x41c00000, v52
	v_rndne_f32_e32 v42, v42
	v_med3_f32 v41, v41, s12, v151
	v_mul_f32_e32 v46, 0x41c00000, v50
	v_rndne_f32_e32 v47, v47
	v_mul_f32_e32 v48, 0x41c00000, v51
	v_med3_f32 v49, v49, s12, v151
	v_cvt_i32_f32_sdwa v50, v42 dst_sel:WORD_1 dst_unused:UNUSED_PAD src0_sel:DWORD
	v_mul_f32_e32 v42, 0x41c00000, v53
	v_rndne_f32_e32 v41, v41
	v_cvt_i32_f32_e32 v47, v47
	v_med3_f32 v48, v48, s12, v151
	v_rndne_f32_e32 v49, v49
	v_med3_f32 v42, v42, s12, v151
	v_cvt_i32_f32_e32 v41, v41
	v_med3_f32 v46, v46, s12, v151
	v_rndne_f32_e32 v48, v48
	v_cvt_i32_f32_sdwa v49, v49 dst_sel:WORD_1 dst_unused:UNUSED_PAD src0_sel:DWORD
	v_rndne_f32_e32 v42, v42
	v_mul_f32_e32 v43, 0x41c00000, v43
	v_rndne_f32_e32 v46, v46
	v_cvt_i32_f32_e32 v48, v48
	v_cvt_i32_f32_sdwa v42, v42 dst_sel:BYTE_3 dst_unused:UNUSED_PAD src0_sel:DWORD
	v_med3_f32 v43, v43, s12, v151
	v_cvt_i32_f32_e32 v46, v46
	v_rndne_f32_e32 v43, v43
	v_cvt_i32_f32_sdwa v43, v43 dst_sel:BYTE_3 dst_unused:UNUSED_PAD src0_sel:DWORD
	v_lshlrev_b32_e32 v47, 8, v47
	v_and_b32_e32 v49, 0xff0000, v49
	v_perm_b32 v41, v47, v41, s15
	v_or3_b32 v42, v41, v42, v49
	v_lshlrev_b32_e32 v41, 8, v48
	v_and_b32_e32 v47, 0xff0000, v50
	v_perm_b32 v41, v41, v46, s15
	v_or3_b32 v43, v41, v43, v47
	global_store_dwordx2 v[44:45], v[42:43], off offset:3072
	global_load_dwordx4 v[46:49], v[88:89], off
	global_load_dwordx4 v[50:53], v[90:91], off
	global_load_dwordx4 v[54:57], v[88:89], off offset:16
	global_load_dwordx4 v[58:61], v[90:91], off offset:16
	v_pk_mul_f32 v[38:39], v[38:39], v[40:41] op_sel_hi:[1,0]
	v_pk_mul_f32 v[36:37], v[36:37], v[40:41] op_sel_hi:[1,0]
	v_pk_mul_f32 v[34:35], v[34:35], v[40:41] op_sel_hi:[1,0]
	v_pk_mul_f32 v[32:33], v[32:33], v[40:41] op_sel_hi:[1,0]
	s_waitcnt vmcnt(3)
	v_mov_b32_e32 v42, v46
	v_mov_b32_e32 v43, v48
	s_waitcnt vmcnt(2)
	v_mov_b32_e32 v62, v50
	v_mov_b32_e32 v63, v52
	v_mov_b32_e32 v48, v47
	v_mov_b32_e32 v52, v51
	v_pk_fma_f32 v[38:39], v[38:39], v[42:43], v[62:63]
	v_pk_fma_f32 v[36:37], v[36:37], v[48:49], v[52:53]
	s_waitcnt vmcnt(1)
	v_mov_b32_e32 v42, v54
	v_mov_b32_e32 v43, v56
	s_waitcnt vmcnt(0)
	v_mov_b32_e32 v46, v58
	v_mov_b32_e32 v47, v60
	v_pk_fma_f32 v[42:43], v[34:35], v[42:43], v[46:47]
	v_mov_b32_e32 v56, v55
	v_mov_b32_e32 v60, v59
	v_bfe_u32 v34, v37, 16, 1
	v_bfe_u32 v35, v36, 16, 1
	v_pk_fma_f32 v[40:41], v[32:33], v[56:57], v[60:61]
	v_add3_u32 v46, v36, v35, s3
	v_add3_u32 v47, v37, v34, s3
	v_bfe_u32 v34, v38, 16, 1
	v_bfe_u32 v35, v39, 16, 1
	v_bfe_u32 v48, v42, 16, 1
	v_bfe_u32 v49, v43, 16, 1
	v_bfe_u32 v32, v41, 16, 1
	v_bfe_u32 v33, v40, 16, 1
	v_add3_u32 v49, v43, v49, s3
	v_add3_u32 v48, v42, v48, s3
	v_add3_u32 v35, v39, v35, s3
	v_add3_u32 v34, v38, v34, s3
	v_add3_u32 v33, v40, v33, s3
	v_add3_u32 v32, v41, v32, s3
	v_lshrrev_b32_e32 v50, 16, v34
	v_lshrrev_b32_e32 v51, 16, v35
	v_lshrrev_b32_e32 v34, 16, v48
	v_lshrrev_b32_e32 v35, 16, v49
	v_and_or_b32 v35, v32, s1, v35
	v_and_or_b32 v34, v33, s1, v34
	v_and_or_b32 v33, v47, s1, v51
	v_and_or_b32 v32, v46, s1, v50
	v_lshl_add_u64 v[46:47], s[18:19], 0, v[96:97]
	global_store_dwordx4 v[46:47], v[32:35], off
	v_mov_b64_e32 v[50:51], v[2:3]
	v_mov_b64_e32 v[54:55], v[6:7]
	v_mul_f32_e32 v34, 0x41c00000, v39
	v_mul_f32_e32 v32, 0x41c00000, v38
	v_med3_f32 v34, v34, s12, v151
	v_mul_f32_e32 v35, 0x41c00000, v37
	v_med3_f32 v32, v32, s12, v151
	v_mul_f32_e32 v33, 0x41c00000, v36
	v_rndne_f32_e32 v34, v34
	v_med3_f32 v35, v35, s12, v151
	v_mul_f32_e32 v36, 0x41c00000, v42
	v_mul_f32_e32 v37, 0x41c00000, v40
	v_rndne_f32_e32 v32, v32
	v_med3_f32 v33, v33, s12, v151
	v_cvt_i32_f32_e32 v34, v34
	v_rndne_f32_e32 v35, v35
	v_med3_f32 v36, v36, s12, v151
	v_med3_f32 v37, v37, s12, v151
	v_mul_f32_e32 v38, 0x41c00000, v43
	v_mul_f32_e32 v39, 0x41c00000, v41
	v_cvt_i32_f32_e32 v32, v32
	v_rndne_f32_e32 v33, v33
	v_cvt_i32_f32_e32 v35, v35
	v_rndne_f32_e32 v36, v36
	v_rndne_f32_e32 v37, v37
	v_med3_f32 v38, v38, s12, v151
	v_med3_f32 v39, v39, s12, v151
	v_cvt_i32_f32_e32 v33, v33
	v_cvt_i32_f32_sdwa v36, v36 dst_sel:WORD_1 dst_unused:UNUSED_PAD src0_sel:DWORD
	v_cvt_i32_f32_sdwa v37, v37 dst_sel:WORD_1 dst_unused:UNUSED_PAD src0_sel:DWORD
	v_rndne_f32_e32 v38, v38
	v_rndne_f32_e32 v39, v39
	v_cvt_i32_f32_sdwa v38, v38 dst_sel:BYTE_3 dst_unused:UNUSED_PAD src0_sel:DWORD
	v_cvt_i32_f32_sdwa v39, v39 dst_sel:BYTE_3 dst_unused:UNUSED_PAD src0_sel:DWORD
	v_lshlrev_b32_e32 v34, 8, v34
	v_perm_b32 v32, v34, v32, s15
	v_lshlrev_b32_e32 v34, 8, v35
	v_and_b32_e32 v36, 0xff0000, v36
	v_and_b32_e32 v35, 0xff0000, v37
	v_perm_b32 v33, v34, v33, s15
	v_or3_b32 v32, v32, v38, v36
	v_or3_b32 v33, v33, v39, v35
	global_store_dwordx2 v[44:45], v[32:33], off offset:3584
	v_mov_b64_e32 v[34:35], v[26:27]
	v_mov_b64_e32 v[38:39], v[30:31]
	v_mov_b64_e32 v[42:43], v[18:19]
	v_mov_b64_e32 v[46:47], v[22:23]
	v_mov_b64_e32 v[58:59], v[10:11]
	v_mov_b64_e32 v[62:63], v[14:15]
	v_lshl_add_u64 v[96:97], v[96:97], 0, s[6:7]
	v_mov_b64_e32 v[32:33], v[24:25]
	v_mov_b64_e32 v[36:37], v[28:29]
	v_mov_b64_e32 v[40:41], v[16:17]
	v_mov_b64_e32 v[44:45], v[20:21]
	v_mov_b64_e32 v[48:49], v[0:1]
	v_mov_b64_e32 v[52:53], v[4:5]
	v_mov_b64_e32 v[56:57], v[8:9]
	v_mov_b64_e32 v[60:61], v[12:13]
	s_cbranch_vccz .LBB0_1482
